# norm tail: four column-tile slot reads issued together (were four dependent agent-scope round trips); phase-0 cond staging loads in flight together; DIFF epilogue gain loads hoisted
# baseline (speedup 1.0000x reference)
; __device__ __forceinline__ unsigned pk2(float lo, float hi) { f32x2_t v = {lo, hi}; bf16x2_t b = __builtin_convertvector(v, bf16x2_t); return __builtin_bit_cast(unsigned, b); }
; __device__ __forceinline__ void fused_norm_tail(CA& A, int l, int s) {
;     ...
;     const f32x4 ca = *(const f32x4*)(A.norm_g + (size_t)nsite * DM + col) * (1.0f + *(const f32x4*)(MODn + DM + col)), cb = *(const f32x4*)(MODn + col);
;     if (tid == 0) {
;         __hip_atomic_fetch_add(cnt, 1u, __ATOMIC_RELAXED, __HIP_MEMORY_SCOPE_AGENT);
;         unsigned spins = 0;
;         while (__hip_atomic_load(cnt, __ATOMIC_RELAXED, __HIP_MEMORY_SCOPE_AGENT) < 4u) { __builtin_amdgcn_s_sleep(2); if (++spins > (1u << 22)) break; }
;     }
;     __syncthreads();
;     float rstd_l = 0.f;
;     {
;         const int row = u.pm * 256 + wave * 32 + (lane & 31);
;         float ss = 0.f;
; #pragma unroll
;         for (int t = 0; t < 4; ++t) {
;             const unsigned long long* sp = (const unsigned long long*)(slots + ((size_t)t * M + row) * 4);
;             const unsigned long long w0 = __hip_atomic_load(sp, __ATOMIC_RELAXED, __HIP_MEMORY_SCOPE_AGENT), w1 = __hip_atomic_load(sp + 1, __ATOMIC_RELAXED, __HIP_MEMORY_SCOPE_AGENT);
;             ss += (__uint_as_float((unsigned)w0) + __uint_as_float((unsigned)(w0 >> 32))) + (__uint_as_float((unsigned)w1) + __uint_as_float((unsigned)(w1 >> 32)));
;         }
;         rstd_l = rsqrtf(ss * (1.0f / DM) + EPS);
;     }
; #pragma unroll
;     for (int r = 0; r < 32; ++r) {
;         const int row = u.pm * 256 + wave * 32 + r;
;         const float rstd = __builtin_bit_cast(float, __builtin_amdgcn_readlane(__builtin_bit_cast(int, rstd_l), r));
;         const f32x4 y = hrow[r] * rstd * ca + cb;
;         v2u o; o.x = pk2(y.x, y.y); o.y = pk2(y.z, y.w);
;         *(v2u*)(xn + (size_t)row * DM + col) = o;
;     }
.LBB0_149:
	s_or_b64 exec, exec, s[84:85]
	s_lshl_b64 s[80:81], s[80:81], 20
	v_readlane_b32 s82, v236, 1
	s_waitcnt vmcnt(1)
	v_pk_add_f32 v[138:139], v[138:139], 1.0 op_sel_hi:[1,0]
	v_readlane_b32 s83, v236, 2
	s_add_u32 s80, s82, s80
	v_pk_mul_f32 v[134:135], v[134:135], v[138:139]
	v_and_or_b32 v138, v1, 31, s78
	s_addc_u32 s81, s83, s81
	v_ashrrev_i32_e32 v139, 31, v138
	v_lshl_add_u64 v[138:139], v[138:139], 4, s[80:81]
	s_mov_b32 s20, 0xed00000
	v_pk_add_f32 v[140:141], v[140:141], 1.0 op_sel_hi:[1,0]
	s_mov_b64 s[80:81], 0xed00000
	v_add_co_u32_e32 v144, vcc, s20, v138
	v_pk_mul_f32 v[136:137], v[136:137], v[140:141]
	v_lshl_add_u64 v[140:141], v[138:139], 0, s[80:81]
	v_addc_co_u32_e32 v145, vcc, 0, v139, vcc
	s_barrier
	global_load_dwordx2 v[144:145], v[144:145], off sc1
	s_mov_b64 s[80:81], 0xed40000
	global_load_dwordx2 v[140:141], v[140:141], off offset:8 sc1
	v_lshl_add_u64 v[146:147], v[138:139], 0, s[80:81]
	s_mov_b64 s[80:81], 0xed80000
	v_lshl_add_u64 v[150:151], v[138:139], 0, s[80:81]
	s_mov_b64 s[80:81], 0xedc0000
	v_lshl_add_u64 v[154:155], v[138:139], 0, s[80:81]
	global_load_dwordx2 v[148:149], v[146:147], off sc1
	global_load_dwordx2 v[146:147], v[146:147], off offset:8 sc1
	global_load_dwordx2 v[152:153], v[150:151], off sc1
	global_load_dwordx2 v[150:151], v[150:151], off offset:8 sc1
	global_load_dwordx2 v[156:157], v[154:155], off sc1
	global_load_dwordx2 v[154:155], v[154:155], off offset:8 sc1
	s_lshl_b64 s[4:5], s[4:5], 11
	s_mov_b32 s88, s6
	s_mov_b32 s20, 0xedc0000
	s_mov_b64 s[80:81], 0xed00000
	s_waitcnt vmcnt(0)
	v_add_f32_e32 v1, v144, v145
	v_add_f32_e32 v140, v140, v141
	v_add_f32_e32 v1, v1, v140
	v_add_f32_e32 v1, 0, v1
	v_add_f32_e32 v144, v148, v149
	v_add_f32_e32 v140, v146, v147
	v_add_f32_e32 v140, v144, v140
	v_add_f32_e32 v1, v1, v140
	v_add_f32_e32 v144, v152, v153
	v_add_f32_e32 v140, v150, v151
	v_add_f32_e32 v140, v144, v140
	v_add_f32_e32 v1, v1, v140
	v_add_f32_e32 v140, v156, v157
	v_add_f32_e32 v138, v154, v155
	v_add_f32_e32 v138, v140, v138
	v_add_f32_e32 v1, v1, v138
	v_fmamk_f32 v1, v1, 0x3a800000, v216
	v_cmp_gt_f32_e32 vcc, s0, v1
	v_mul_f32_e32 v138, 0x4b800000, v1
	s_nop 0
	v_cndmask_b32_e32 v1, v1, v138, vcc
	v_rsq_f32_e32 v1, v1
	s_nop 0
	v_mul_f32_e32 v138, 0x45800000, v1
	v_cndmask_b32_e32 v1, v1, v138, vcc
	v_lshl_add_u64 v[138:139], v[142:143], 1, s[8:9]
	v_readlane_b32 s8, v1, 0
	s_nop 1
	v_pk_mul_f32 v[126:127], v[126:127], s[8:9] op_sel_hi:[1,0]
	v_pk_mul_f32 v[128:129], v[128:129], s[8:9] op_sel_hi:[1,0]
	v_pk_fma_f32 v[126:127], v[134:135], v[126:127], v[130:131]
	v_pk_fma_f32 v[128:129], v[136:137], v[128:129], v[132:133]
	s_lshl_b64 s[8:9], s[78:79], 11
	v_cvt_pk_bf16_f32 v126, v126, v127
	v_cvt_pk_bf16_f32 v127, v128, v129
	v_lshl_add_u64 v[128:129], v[138:139], 0, s[8:9]
	v_readlane_b32 s8, v1, 1
	global_store_dwordx2 v[128:129], v[126:127], off
	s_nop 0
	v_pk_mul_f32 v[122:123], v[122:123], s[8:9] op_sel_hi:[1,0]
	v_pk_mul_f32 v[124:125], v[124:125], s[8:9] op_sel_hi:[1,0]
	v_pk_fma_f32 v[122:123], v[134:135], v[122:123], v[130:131]
	v_pk_fma_f32 v[124:125], v[136:137], v[124:125], v[132:133]
	s_lshl_b64 s[8:9], s[76:77], 11
	v_cvt_pk_bf16_f32 v122, v122, v123
	v_cvt_pk_bf16_f32 v123, v124, v125
	v_lshl_add_u64 v[124:125], v[138:139], 0, s[8:9]
	v_readlane_b32 s8, v1, 2
	global_store_dwordx2 v[124:125], v[122:123], off
	s_nop 0
	v_pk_mul_f32 v[118:119], v[118:119], s[8:9] op_sel_hi:[1,0]
	v_pk_mul_f32 v[120:121], v[120:121], s[8:9] op_sel_hi:[1,0]
	v_pk_fma_f32 v[118:119], v[134:135], v[118:119], v[130:131]
	v_pk_fma_f32 v[120:121], v[136:137], v[120:121], v[132:133]
	s_lshl_b64 s[8:9], s[74:75], 11
	v_cvt_pk_bf16_f32 v118, v118, v119
	v_cvt_pk_bf16_f32 v119, v120, v121
	v_lshl_add_u64 v[120:121], v[138:139], 0, s[8:9]
	v_readlane_b32 s8, v1, 3
	global_store_dwordx2 v[120:121], v[118:119], off
	s_nop 0
	v_pk_mul_f32 v[114:115], v[114:115], s[8:9] op_sel_hi:[1,0]
	v_pk_mul_f32 v[116:117], v[116:117], s[8:9] op_sel_hi:[1,0]
	v_pk_fma_f32 v[114:115], v[134:135], v[114:115], v[130:131]
	v_pk_fma_f32 v[116:117], v[136:137], v[116:117], v[132:133]
	s_lshl_b64 s[8:9], s[72:73], 11
	v_cvt_pk_bf16_f32 v114, v114, v115
	v_cvt_pk_bf16_f32 v115, v116, v117
	v_lshl_add_u64 v[116:117], v[138:139], 0, s[8:9]
	v_readlane_b32 s8, v1, 4
	global_store_dwordx2 v[116:117], v[114:115], off
	s_nop 0
	v_pk_mul_f32 v[110:111], v[110:111], s[8:9] op_sel_hi:[1,0]
	v_pk_mul_f32 v[112:113], v[112:113], s[8:9] op_sel_hi:[1,0]
	v_pk_fma_f32 v[110:111], v[134:135], v[110:111], v[130:131]
	v_pk_fma_f32 v[112:113], v[136:137], v[112:113], v[132:133]
	s_lshl_b64 s[8:9], s[70:71], 11
	v_cvt_pk_bf16_f32 v110, v110, v111
	v_cvt_pk_bf16_f32 v111, v112, v113
	v_lshl_add_u64 v[112:113], v[138:139], 0, s[8:9]
	v_readlane_b32 s8, v1, 5
	global_store_dwordx2 v[112:113], v[110:111], off
	s_nop 0
	v_pk_mul_f32 v[106:107], v[106:107], s[8:9] op_sel_hi:[1,0]
	v_pk_mul_f32 v[108:109], v[108:109], s[8:9] op_sel_hi:[1,0]
	v_pk_fma_f32 v[106:107], v[134:135], v[106:107], v[130:131]
	v_pk_fma_f32 v[108:109], v[136:137], v[108:109], v[132:133]
	s_lshl_b64 s[8:9], s[68:69], 11
	v_cvt_pk_bf16_f32 v106, v106, v107
	v_cvt_pk_bf16_f32 v107, v108, v109
	v_lshl_add_u64 v[108:109], v[138:139], 0, s[8:9]
	v_readlane_b32 s8, v1, 6
	global_store_dwordx2 v[108:109], v[106:107], off
	s_nop 0
	v_pk_mul_f32 v[102:103], v[102:103], s[8:9] op_sel_hi:[1,0]
	v_pk_mul_f32 v[104:105], v[104:105], s[8:9] op_sel_hi:[1,0]
	v_pk_fma_f32 v[102:103], v[134:135], v[102:103], v[130:131]
	v_pk_fma_f32 v[104:105], v[136:137], v[104:105], v[132:133]
	s_lshl_b64 s[8:9], s[66:67], 11
	v_cvt_pk_bf16_f32 v102, v102, v103
	v_cvt_pk_bf16_f32 v103, v104, v105
; __device__ __forceinline__ unsigned pk2(float lo, float hi) { f32x2_t v = {lo, hi}; bf16x2_t b = __builtin_convertvector(v, bf16x2_t); return __builtin_bit_cast(unsigned, b); }
; __device__ __forceinline__ void fused_norm_tail(CA& A, int l, int s) {
;     ...
; #pragma unroll
;     for (int r = 0; r < 32; ++r) {
;         const int row = u.pm * 256 + wave * 32 + r;
;         const float rstd = __builtin_bit_cast(float, __builtin_amdgcn_readlane(__builtin_bit_cast(int, rstd_l), r));
;         const f32x4 y = hrow[r] * rstd * ca + cb;
;         v2u o; o.x = pk2(y.x, y.y); o.y = pk2(y.z, y.w);
;         *(v2u*)(xn + (size_t)row * DM + col) = o;
;     }
	v_lshl_add_u64 v[104:105], v[138:139], 0, s[8:9]
	v_readlane_b32 s8, v1, 7
	global_store_dwordx2 v[104:105], v[102:103], off
	s_nop 0
	v_pk_mul_f32 v[98:99], v[98:99], s[8:9] op_sel_hi:[1,0]
	v_pk_mul_f32 v[100:101], v[100:101], s[8:9] op_sel_hi:[1,0]
	v_pk_fma_f32 v[98:99], v[134:135], v[98:99], v[130:131]
	v_pk_fma_f32 v[100:101], v[136:137], v[100:101], v[132:133]
	s_lshl_b64 s[8:9], s[64:65], 11
	v_cvt_pk_bf16_f32 v98, v98, v99
	v_cvt_pk_bf16_f32 v99, v100, v101
	v_lshl_add_u64 v[100:101], v[138:139], 0, s[8:9]
	v_readlane_b32 s8, v1, 8
	global_store_dwordx2 v[100:101], v[98:99], off
	s_nop 0
	v_pk_mul_f32 v[94:95], v[94:95], s[8:9] op_sel_hi:[1,0]
	v_pk_mul_f32 v[96:97], v[96:97], s[8:9] op_sel_hi:[1,0]
	v_pk_fma_f32 v[94:95], v[134:135], v[94:95], v[130:131]
	v_pk_fma_f32 v[96:97], v[136:137], v[96:97], v[132:133]
	s_lshl_b64 s[8:9], s[62:63], 11
	v_cvt_pk_bf16_f32 v94, v94, v95
	v_cvt_pk_bf16_f32 v95, v96, v97
	v_lshl_add_u64 v[96:97], v[138:139], 0, s[8:9]
	v_readlane_b32 s8, v1, 9
	global_store_dwordx2 v[96:97], v[94:95], off
	s_nop 0
	v_pk_mul_f32 v[90:91], v[90:91], s[8:9] op_sel_hi:[1,0]
	v_pk_mul_f32 v[92:93], v[92:93], s[8:9] op_sel_hi:[1,0]
	v_pk_fma_f32 v[90:91], v[134:135], v[90:91], v[130:131]
	v_pk_fma_f32 v[92:93], v[136:137], v[92:93], v[132:133]
	s_lshl_b64 s[8:9], s[60:61], 11
	v_cvt_pk_bf16_f32 v90, v90, v91
	v_cvt_pk_bf16_f32 v91, v92, v93
	v_lshl_add_u64 v[92:93], v[138:139], 0, s[8:9]
	v_readlane_b32 s8, v1, 10
	global_store_dwordx2 v[92:93], v[90:91], off
	s_nop 0
	v_pk_mul_f32 v[86:87], v[86:87], s[8:9] op_sel_hi:[1,0]
	v_pk_mul_f32 v[88:89], v[88:89], s[8:9] op_sel_hi:[1,0]
	v_pk_fma_f32 v[86:87], v[134:135], v[86:87], v[130:131]
	v_pk_fma_f32 v[88:89], v[136:137], v[88:89], v[132:133]
	s_lshl_b64 s[8:9], s[58:59], 11
	v_cvt_pk_bf16_f32 v86, v86, v87
	v_cvt_pk_bf16_f32 v87, v88, v89
	v_lshl_add_u64 v[88:89], v[138:139], 0, s[8:9]
	v_readlane_b32 s8, v1, 11
	global_store_dwordx2 v[88:89], v[86:87], off
	s_nop 0
	v_pk_mul_f32 v[82:83], v[82:83], s[8:9] op_sel_hi:[1,0]
	v_pk_mul_f32 v[84:85], v[84:85], s[8:9] op_sel_hi:[1,0]
	v_pk_fma_f32 v[82:83], v[134:135], v[82:83], v[130:131]
	v_pk_fma_f32 v[84:85], v[136:137], v[84:85], v[132:133]
	s_lshl_b64 s[8:9], s[56:57], 11
	v_cvt_pk_bf16_f32 v82, v82, v83
	v_cvt_pk_bf16_f32 v83, v84, v85
	v_lshl_add_u64 v[84:85], v[138:139], 0, s[8:9]
	v_readlane_b32 s8, v1, 12
	global_store_dwordx2 v[84:85], v[82:83], off
	s_nop 0
	v_pk_mul_f32 v[78:79], v[78:79], s[8:9] op_sel_hi:[1,0]
	v_pk_mul_f32 v[80:81], v[80:81], s[8:9] op_sel_hi:[1,0]
	v_pk_fma_f32 v[78:79], v[134:135], v[78:79], v[130:131]
	v_pk_fma_f32 v[80:81], v[136:137], v[80:81], v[132:133]
	s_lshl_b64 s[8:9], s[54:55], 11
	v_cvt_pk_bf16_f32 v78, v78, v79
	v_cvt_pk_bf16_f32 v79, v80, v81
	v_lshl_add_u64 v[80:81], v[138:139], 0, s[8:9]
	v_readlane_b32 s8, v1, 13
	global_store_dwordx2 v[80:81], v[78:79], off
	s_nop 0
	v_pk_mul_f32 v[74:75], v[74:75], s[8:9] op_sel_hi:[1,0]
	v_pk_mul_f32 v[76:77], v[76:77], s[8:9] op_sel_hi:[1,0]
	v_pk_fma_f32 v[74:75], v[134:135], v[74:75], v[130:131]
	v_pk_fma_f32 v[76:77], v[136:137], v[76:77], v[132:133]
	s_lshl_b64 s[8:9], s[52:53], 11
	v_cvt_pk_bf16_f32 v74, v74, v75
	v_cvt_pk_bf16_f32 v75, v76, v77
	v_lshl_add_u64 v[76:77], v[138:139], 0, s[8:9]
	v_readlane_b32 s8, v1, 14
	global_store_dwordx2 v[76:77], v[74:75], off
	s_nop 0
	v_pk_mul_f32 v[70:71], v[70:71], s[8:9] op_sel_hi:[1,0]
	v_pk_mul_f32 v[72:73], v[72:73], s[8:9] op_sel_hi:[1,0]
	v_pk_fma_f32 v[70:71], v[134:135], v[70:71], v[130:131]
	v_pk_fma_f32 v[72:73], v[136:137], v[72:73], v[132:133]
	s_lshl_b64 s[8:9], s[50:51], 11
	v_cvt_pk_bf16_f32 v70, v70, v71
	v_cvt_pk_bf16_f32 v71, v72, v73
	v_lshl_add_u64 v[72:73], v[138:139], 0, s[8:9]
	v_readlane_b32 s8, v1, 15
	global_store_dwordx2 v[72:73], v[70:71], off
	s_nop 0
	v_pk_mul_f32 v[66:67], v[66:67], s[8:9] op_sel_hi:[1,0]
	v_pk_mul_f32 v[68:69], v[68:69], s[8:9] op_sel_hi:[1,0]
	v_pk_fma_f32 v[66:67], v[134:135], v[66:67], v[130:131]
	v_pk_fma_f32 v[68:69], v[136:137], v[68:69], v[132:133]
	s_lshl_b64 s[8:9], s[48:49], 11
	v_cvt_pk_bf16_f32 v66, v66, v67
	v_cvt_pk_bf16_f32 v67, v68, v69
	v_lshl_add_u64 v[68:69], v[138:139], 0, s[8:9]
	v_readlane_b32 s8, v1, 16
	global_store_dwordx2 v[68:69], v[66:67], off
	s_nop 0
	v_pk_mul_f32 v[62:63], v[62:63], s[8:9] op_sel_hi:[1,0]
	v_pk_mul_f32 v[64:65], v[64:65], s[8:9] op_sel_hi:[1,0]
	v_pk_fma_f32 v[62:63], v[134:135], v[62:63], v[130:131]
	v_pk_fma_f32 v[64:65], v[136:137], v[64:65], v[132:133]
	s_lshl_b64 s[8:9], s[46:47], 11
	v_cvt_pk_bf16_f32 v62, v62, v63
	v_cvt_pk_bf16_f32 v63, v64, v65
	v_lshl_add_u64 v[64:65], v[138:139], 0, s[8:9]
	v_readlane_b32 s8, v1, 17
	global_store_dwordx2 v[64:65], v[62:63], off
	s_nop 0
	v_pk_mul_f32 v[58:59], v[58:59], s[8:9] op_sel_hi:[1,0]
	v_pk_mul_f32 v[60:61], v[60:61], s[8:9] op_sel_hi:[1,0]
	v_pk_fma_f32 v[58:59], v[134:135], v[58:59], v[130:131]
	v_pk_fma_f32 v[60:61], v[136:137], v[60:61], v[132:133]
	s_lshl_b64 s[8:9], s[44:45], 11
	v_cvt_pk_bf16_f32 v58, v58, v59
	v_cvt_pk_bf16_f32 v59, v60, v61
	v_lshl_add_u64 v[60:61], v[138:139], 0, s[8:9]
	v_readlane_b32 s8, v1, 18
	global_store_dwordx2 v[60:61], v[58:59], off
	s_nop 0
	v_pk_mul_f32 v[54:55], v[54:55], s[8:9] op_sel_hi:[1,0]
	v_pk_mul_f32 v[56:57], v[56:57], s[8:9] op_sel_hi:[1,0]
	v_pk_fma_f32 v[54:55], v[134:135], v[54:55], v[130:131]
	v_pk_fma_f32 v[56:57], v[136:137], v[56:57], v[132:133]
	s_lshl_b64 s[8:9], s[42:43], 11
	v_cvt_pk_bf16_f32 v54, v54, v55
	v_cvt_pk_bf16_f32 v55, v56, v57
	v_lshl_add_u64 v[56:57], v[138:139], 0, s[8:9]
	v_readlane_b32 s8, v1, 19
	global_store_dwordx2 v[56:57], v[54:55], off
	s_nop 0
; __device__ __forceinline__ unsigned pk2(float lo, float hi) { f32x2_t v = {lo, hi}; bf16x2_t b = __builtin_convertvector(v, bf16x2_t); return __builtin_bit_cast(unsigned, b); }
; __device__ __forceinline__ void fused_norm_tail(CA& A, int l, int s) {
;     ...
; #pragma unroll
;     for (int r = 0; r < 32; ++r) {
;         const int row = u.pm * 256 + wave * 32 + r;
;         const float rstd = __builtin_bit_cast(float, __builtin_amdgcn_readlane(__builtin_bit_cast(int, rstd_l), r));
;         const f32x4 y = hrow[r] * rstd * ca + cb;
;         v2u o; o.x = pk2(y.x, y.y); o.y = pk2(y.z, y.w);
;         *(v2u*)(xn + (size_t)row * DM + col) = o;
;     }
	v_pk_mul_f32 v[50:51], v[50:51], s[8:9] op_sel_hi:[1,0]
	v_pk_mul_f32 v[52:53], v[52:53], s[8:9] op_sel_hi:[1,0]
	v_pk_fma_f32 v[50:51], v[134:135], v[50:51], v[130:131]
	v_pk_fma_f32 v[52:53], v[136:137], v[52:53], v[132:133]
	s_lshl_b64 s[8:9], s[40:41], 11
	v_cvt_pk_bf16_f32 v50, v50, v51
	v_cvt_pk_bf16_f32 v51, v52, v53
	v_lshl_add_u64 v[52:53], v[138:139], 0, s[8:9]
	v_readlane_b32 s8, v1, 20
	global_store_dwordx2 v[52:53], v[50:51], off
	s_nop 0
	v_pk_mul_f32 v[46:47], v[46:47], s[8:9] op_sel_hi:[1,0]
	v_pk_mul_f32 v[48:49], v[48:49], s[8:9] op_sel_hi:[1,0]
	v_pk_fma_f32 v[46:47], v[134:135], v[46:47], v[130:131]
	v_pk_fma_f32 v[48:49], v[136:137], v[48:49], v[132:133]
	s_lshl_b64 s[8:9], s[38:39], 11
	v_cvt_pk_bf16_f32 v46, v46, v47
	v_cvt_pk_bf16_f32 v47, v48, v49
	v_lshl_add_u64 v[48:49], v[138:139], 0, s[8:9]
	v_readlane_b32 s8, v1, 21
	global_store_dwordx2 v[48:49], v[46:47], off
	s_nop 0
	v_pk_mul_f32 v[42:43], v[42:43], s[8:9] op_sel_hi:[1,0]
	v_pk_mul_f32 v[44:45], v[44:45], s[8:9] op_sel_hi:[1,0]
	v_pk_fma_f32 v[42:43], v[134:135], v[42:43], v[130:131]
	v_pk_fma_f32 v[44:45], v[136:137], v[44:45], v[132:133]
	s_lshl_b64 s[8:9], s[34:35], 11
	v_cvt_pk_bf16_f32 v42, v42, v43
	v_cvt_pk_bf16_f32 v43, v44, v45
	v_lshl_add_u64 v[44:45], v[138:139], 0, s[8:9]
	v_readlane_b32 s8, v1, 22
	global_store_dwordx2 v[44:45], v[42:43], off
	s_nop 0
	v_pk_mul_f32 v[38:39], v[38:39], s[8:9] op_sel_hi:[1,0]
	v_pk_mul_f32 v[40:41], v[40:41], s[8:9] op_sel_hi:[1,0]
	v_pk_fma_f32 v[38:39], v[134:135], v[38:39], v[130:131]
	v_pk_fma_f32 v[40:41], v[136:137], v[40:41], v[132:133]
	s_lshl_b64 s[8:9], s[30:31], 11
	v_cvt_pk_bf16_f32 v38, v38, v39
	v_cvt_pk_bf16_f32 v39, v40, v41
	v_lshl_add_u64 v[40:41], v[138:139], 0, s[8:9]
	v_readlane_b32 s8, v1, 23
	global_store_dwordx2 v[40:41], v[38:39], off
	s_nop 0
	v_pk_mul_f32 v[34:35], v[34:35], s[8:9] op_sel_hi:[1,0]
	v_pk_mul_f32 v[36:37], v[36:37], s[8:9] op_sel_hi:[1,0]
	v_pk_fma_f32 v[34:35], v[134:135], v[34:35], v[130:131]
	v_pk_fma_f32 v[36:37], v[136:137], v[36:37], v[132:133]
	s_lshl_b64 s[8:9], s[28:29], 11
	v_cvt_pk_bf16_f32 v34, v34, v35
	v_cvt_pk_bf16_f32 v35, v36, v37
	v_lshl_add_u64 v[36:37], v[138:139], 0, s[8:9]
	v_readlane_b32 s8, v1, 24
	global_store_dwordx2 v[36:37], v[34:35], off
	s_nop 0
	v_pk_mul_f32 v[30:31], v[30:31], s[8:9] op_sel_hi:[1,0]
	v_pk_mul_f32 v[32:33], v[32:33], s[8:9] op_sel_hi:[1,0]
	v_pk_fma_f32 v[30:31], v[134:135], v[30:31], v[130:131]
	v_pk_fma_f32 v[32:33], v[136:137], v[32:33], v[132:133]
	s_lshl_b64 s[8:9], s[26:27], 11
	v_cvt_pk_bf16_f32 v30, v30, v31
	v_cvt_pk_bf16_f32 v31, v32, v33
	v_lshl_add_u64 v[32:33], v[138:139], 0, s[8:9]
	v_readlane_b32 s8, v1, 25
	global_store_dwordx2 v[32:33], v[30:31], off
	s_nop 0
	v_pk_mul_f32 v[26:27], v[26:27], s[8:9] op_sel_hi:[1,0]
	v_pk_mul_f32 v[28:29], v[28:29], s[8:9] op_sel_hi:[1,0]
	v_pk_fma_f32 v[26:27], v[134:135], v[26:27], v[130:131]
	v_pk_fma_f32 v[28:29], v[136:137], v[28:29], v[132:133]
	s_lshl_b64 s[8:9], s[24:25], 11
	v_cvt_pk_bf16_f32 v26, v26, v27
	v_cvt_pk_bf16_f32 v27, v28, v29
	v_lshl_add_u64 v[28:29], v[138:139], 0, s[8:9]
	v_readlane_b32 s8, v1, 26
	global_store_dwordx2 v[28:29], v[26:27], off
	s_nop 0
	v_pk_mul_f32 v[22:23], v[22:23], s[8:9] op_sel_hi:[1,0]
	v_pk_mul_f32 v[24:25], v[24:25], s[8:9] op_sel_hi:[1,0]
	v_pk_fma_f32 v[22:23], v[134:135], v[22:23], v[130:131]
	v_pk_fma_f32 v[24:25], v[136:137], v[24:25], v[132:133]
	s_lshl_b64 s[8:9], s[18:19], 11
	v_cvt_pk_bf16_f32 v22, v22, v23
	v_cvt_pk_bf16_f32 v23, v24, v25
	v_lshl_add_u64 v[24:25], v[138:139], 0, s[8:9]
	v_readlane_b32 s8, v1, 27
	global_store_dwordx2 v[24:25], v[22:23], off
	s_nop 0
	v_pk_mul_f32 v[18:19], v[18:19], s[8:9] op_sel_hi:[1,0]
	v_pk_mul_f32 v[20:21], v[20:21], s[8:9] op_sel_hi:[1,0]
	v_pk_fma_f32 v[18:19], v[134:135], v[18:19], v[130:131]
	v_pk_fma_f32 v[20:21], v[136:137], v[20:21], v[132:133]
	s_lshl_b64 s[8:9], s[16:17], 11
	v_cvt_pk_bf16_f32 v18, v18, v19
	v_cvt_pk_bf16_f32 v19, v20, v21
	v_lshl_add_u64 v[20:21], v[138:139], 0, s[8:9]
	v_readlane_b32 s8, v1, 28
	global_store_dwordx2 v[20:21], v[18:19], off
	s_nop 0
	v_pk_mul_f32 v[14:15], v[14:15], s[8:9] op_sel_hi:[1,0]
	v_pk_mul_f32 v[16:17], v[16:17], s[8:9] op_sel_hi:[1,0]
	v_pk_fma_f32 v[14:15], v[134:135], v[14:15], v[130:131]
	v_pk_fma_f32 v[16:17], v[136:137], v[16:17], v[132:133]
	s_lshl_b64 s[8:9], s[14:15], 11
	v_cvt_pk_bf16_f32 v14, v14, v15
	v_cvt_pk_bf16_f32 v15, v16, v17
	v_lshl_add_u64 v[16:17], v[138:139], 0, s[8:9]
	v_readlane_b32 s8, v1, 29
	global_store_dwordx2 v[16:17], v[14:15], off
	s_nop 0
	v_pk_mul_f32 v[10:11], v[10:11], s[8:9] op_sel_hi:[1,0]
	v_pk_mul_f32 v[12:13], v[12:13], s[8:9] op_sel_hi:[1,0]
	v_pk_fma_f32 v[10:11], v[134:135], v[10:11], v[130:131]
	v_pk_fma_f32 v[12:13], v[136:137], v[12:13], v[132:133]
	s_lshl_b64 s[8:9], s[12:13], 11
	v_cvt_pk_bf16_f32 v10, v10, v11
	v_cvt_pk_bf16_f32 v11, v12, v13
	v_lshl_add_u64 v[12:13], v[138:139], 0, s[8:9]
	v_readlane_b32 s8, v1, 30
	global_store_dwordx2 v[12:13], v[10:11], off
	s_nop 0
	v_pk_mul_f32 v[6:7], v[6:7], s[8:9] op_sel_hi:[1,0]
	v_pk_mul_f32 v[8:9], v[8:9], s[8:9] op_sel_hi:[1,0]
	v_pk_fma_f32 v[6:7], v[134:135], v[6:7], v[130:131]
	v_pk_fma_f32 v[8:9], v[136:137], v[8:9], v[132:133]
	s_lshl_b64 s[8:9], s[10:11], 11
	v_cvt_pk_bf16_f32 v6, v6, v7
	v_cvt_pk_bf16_f32 v7, v8, v9
	v_lshl_add_u64 v[8:9], v[138:139], 0, s[8:9]
	v_readlane_b32 s8, v1, 31
	global_store_dwordx2 v[8:9], v[6:7], off
	s_nop 0
	v_pk_mul_f32 v[2:3], v[2:3], s[8:9] op_sel_hi:[1,0]
	v_pk_mul_f32 v[4:5], v[4:5], s[8:9] op_sel_hi:[1,0]
	v_pk_fma_f32 v[2:3], v[134:135], v[2:3], v[130:131]
	v_pk_fma_f32 v[4:5], v[136:137], v[4:5], v[132:133]
	v_cvt_pk_bf16_f32 v2, v2, v3
	v_cvt_pk_bf16_f32 v3, v4, v5
	v_lshl_add_u64 v[4:5], v[138:139], 0, s[4:5]
	global_store_dwordx2 v[4:5], v[2:3], off

; __device__ __forceinline__ float shx(float v, int o) { const int idx = (((int)otid() & 63) ^ o) << 2; return __builtin_bit_cast(float, __builtin_amdgcn_ds_bpermute(idx, __builtin_bit_cast(int, v))); }
; __device__ __forceinline__ unsigned pk2(float lo, float hi) { f32x2_t v = {lo, hi}; bf16x2_t b = __builtin_convertvector(v, bf16x2_t); return __builtin_bit_cast(unsigned, b); }
; __device__ __forceinline__ int crow(int r, int hi) { return (r & 3) + 8 * (r >> 2) + 4 * hi; }
; template <bool DIFF>
; __device__ __forceinline__ void attn_unit(CA& A, int l, int b, int hh, int qb, LAS unsigned char* lds, float lam, float lam_init) {
;     ...
;         __syncthreads();
;         if (strm == 0) {
;             float ss = 0.f;
; #pragma unroll
;             for (int dt = 0; dt < 2; ++dt)
; #pragma unroll
;                 for (int r = 0; r < 16; ++r) { const float v = o[dt][r] * inv - lam * O2[(wq + r32) * 65 + 32 * dt + crow(r, hi)]; o[dt][r] = v; ss += v * v; }
;             ss += shx(ss, 32);
;             const float rs = rsqrtf(ss * (1.0f / 64.0f) + EPS) * (1.0f - lam_init);
;             const float* og = A.diff_out_g + l * 64;
; #pragma unroll
;             for (int dt = 0; dt < 2; ++dt)
; #pragma unroll
;                 for (int g = 0; g < 4; ++g) { const int d = 32 * dt + 8 * g + 4 * hi;
;                     v2u w; w.x = pk2(o[dt][4 * g] * rs * og[d], o[dt][4 * g + 1] * rs * og[d + 1]); w.y = pk2(o[dt][4 * g + 2] * rs * og[d + 2], o[dt][4 * g + 3] * rs * og[d + 3]);
;                     *(v2u*)(MIX + orow * DM + hh * 64 + d) = w; }
.LBB0_753:
	s_cmpk_gt_u32 s17, 0xff
	s_waitcnt lgkmcnt(0)
	s_barrier
	s_cbranch_scc1 .LBB0_755
	s_lshl_b32 s4, s16, 12
	s_add_i32 s19, s19, s4
	s_or_b32 s4, s20, s19
	v_or_b32_e32 v1, s4, v137
	v_or_b32_e32 v3, s18, v137
	s_movk_i32 s4, 0x104
	v_mul_lo_u32 v3, v3, s4
	v_add3_u32 v3, 0, v3, v130
	v_add_u32_e32 v4, 0x94e0, v3
	ds_read2_b32 v[4:5], v4 offset1:1
	v_add_u32_e32 v48, 0x9400, v3
	v_add_u32_e32 v10, 0x9408, v3
	v_add_u32_e32 v49, 0x9420, v3
	v_add_u32_e32 v11, 0x9428, v3
	v_add_u32_e32 v56, 0x9440, v3
	v_add_u32_e32 v54, 0x9448, v3
	v_add_u32_e32 v55, 0x9460, v3
	v_add_u32_e32 v57, 0x9468, v3
	v_add_u32_e32 v64, 0x9480, v3
	v_add_u32_e32 v58, 0x9488, v3
	v_add_u32_e32 v62, 0x94a0, v3
	v_add_u32_e32 v60, 0x94a8, v3
	v_add_u32_e32 v66, 0x94c0, v3
	v_add_u32_e32 v6, 0x94c8, v3
	v_add_u32_e32 v3, 0x94e8, v3
	ds_read2_b32 v[8:9], v3 offset1:1
	ds_read2_b32 v[12:13], v6 offset1:1
	s_waitcnt lgkmcnt(2)
	v_pk_mul_f32 v[4:5], v[128:129], v[4:5]
	v_mov_b32_e32 v72, v179
	v_pk_fma_f32 v[6:7], v[28:29], v[2:3], v[4:5] op_sel_hi:[1,0,1] neg_lo:[0,0,1] neg_hi:[0,0,1]
	s_waitcnt lgkmcnt(1)
	v_pk_mul_f32 v[4:5], v[128:129], v[8:9]
	v_readlane_b32 s10, v237, 58
	v_pk_fma_f32 v[4:5], v[30:31], v[2:3], v[4:5] op_sel_hi:[1,0,1] neg_lo:[0,0,1] neg_hi:[0,0,1]
	ds_read2_b32 v[8:9], v10 offset1:1
	ds_read2_b32 v[10:11], v11 offset1:1
	ds_read2_b32 v[30:31], v49 offset1:1
	ds_read2_b32 v[48:49], v48 offset1:1
	s_lshl_b32 s10, s15, 1
	s_waitcnt lgkmcnt(3)
	v_pk_mul_f32 v[8:9], v[128:129], v[8:9]
	v_lshlrev_b32_e32 v73, 2, v131
	v_pk_fma_f32 v[34:35], v[34:35], v[2:3], v[8:9] op_sel_hi:[1,0,1] neg_lo:[0,0,1] neg_hi:[0,0,1]
	s_waitcnt lgkmcnt(0)
	v_pk_mul_f32 v[8:9], v[128:129], v[48:49]
	v_pk_mul_f32 v[50:51], v[34:35], v[34:35]
	v_pk_fma_f32 v[32:33], v[32:33], v[2:3], v[8:9] op_sel_hi:[1,0,1] neg_lo:[0,0,1] neg_hi:[0,0,1]
	v_pk_mul_f32 v[8:9], v[128:129], v[10:11]
	v_pk_mul_f32 v[48:49], v[32:33], v[32:33]
	v_pk_fma_f32 v[38:39], v[38:39], v[2:3], v[8:9] op_sel_hi:[1,0,1] neg_lo:[0,0,1] neg_hi:[0,0,1]
	v_pk_mul_f32 v[8:9], v[128:129], v[30:31]
	ds_read2_b32 v[10:11], v54 offset1:1
	ds_read2_b32 v[30:31], v57 offset1:1
	ds_read2_b32 v[54:55], v55 offset1:1
	ds_read2_b32 v[56:57], v56 offset1:1
	ds_read2_b32 v[58:59], v58 offset1:1
	ds_read2_b32 v[60:61], v60 offset1:1
	ds_read2_b32 v[62:63], v62 offset1:1
	ds_read2_b32 v[64:65], v64 offset1:1
	ds_read2_b32 v[66:67], v66 offset1:1
	s_load_dwordx2 s[4:5], s[34:35], 0x68
	v_pk_fma_f32 v[36:37], v[36:37], v[2:3], v[8:9] op_sel_hi:[1,0,1] neg_lo:[0,0,1] neg_hi:[0,0,1]
	s_waitcnt lgkmcnt(0)
	v_pk_mul_f32 v[8:9], v[128:129], v[10:11]
	v_add_f32_e32 v48, v48, v49
	v_pk_fma_f32 v[42:43], v[42:43], v[2:3], v[8:9] op_sel_hi:[1,0,1] neg_lo:[0,0,1] neg_hi:[0,0,1]
	s_add_u32 s4, s4, s8
	s_addc_u32 s5, s5, s9
	global_load_dwordx4 v[8:11], v73, s[4:5]
	global_load_dwordx4 v[148:151], v73, s[4:5] offset:32
	global_load_dwordx4 v[152:155], v73, s[4:5] offset:64
	global_load_dwordx4 v[156:159], v73, s[4:5] offset:96
	global_load_dwordx4 v[160:163], v73, s[4:5] offset:128
	global_load_dwordx4 v[164:167], v73, s[4:5] offset:160
	global_load_dwordx4 v[168:171], v73, s[4:5] offset:192
	global_load_dwordx4 v[172:175], v73, s[4:5] offset:224
	v_add_f32_e32 v48, v48, v50
	v_pk_mul_f32 v[68:69], v[36:37], v[36:37]
	v_add_f32_e32 v48, v48, v51
	v_add_f32_e32 v48, v48, v68
	v_pk_mul_f32 v[52:53], v[38:39], v[38:39]
	v_pk_mul_f32 v[56:57], v[128:129], v[56:57]
	v_add_f32_e32 v48, v48, v69
	v_pk_fma_f32 v[40:41], v[40:41], v[2:3], v[56:57] op_sel_hi:[1,0,1] neg_lo:[0,0,1] neg_hi:[0,0,1]
	v_add_f32_e32 v48, v48, v52
	v_pk_mul_f32 v[56:57], v[40:41], v[40:41]
	v_add_f32_e32 v48, v48, v53
	v_add_f32_e32 v48, v48, v56
	v_pk_mul_f32 v[70:71], v[42:43], v[42:43]
	v_pk_mul_f32 v[54:55], v[128:129], v[54:55]
	v_add_f32_e32 v48, v48, v57
	v_pk_fma_f32 v[44:45], v[44:45], v[2:3], v[54:55] op_sel_hi:[1,0,1] neg_lo:[0,0,1] neg_hi:[0,0,1]
	v_add_f32_e32 v48, v48, v70
	v_pk_mul_f32 v[30:31], v[128:129], v[30:31]
	v_pk_mul_f32 v[54:55], v[44:45], v[44:45]
	v_add_f32_e32 v48, v48, v71
	v_pk_fma_f32 v[30:31], v[46:47], v[2:3], v[30:31] op_sel_hi:[1,0,1] neg_lo:[0,0,1] neg_hi:[0,0,1]
	v_add_f32_e32 v48, v48, v54
	v_pk_mul_f32 v[46:47], v[30:31], v[30:31]
	v_pk_mul_f32 v[64:65], v[128:129], v[64:65]
	v_add_f32_e32 v48, v48, v55
	v_pk_fma_f32 v[16:17], v[16:17], v[2:3], v[64:65] op_sel_hi:[1,0,1] neg_lo:[0,0,1] neg_hi:[0,0,1]
	v_add_f32_e32 v46, v48, v46
	v_pk_mul_f32 v[58:59], v[128:129], v[58:59]
	v_pk_mul_f32 v[64:65], v[16:17], v[16:17]
	v_add_f32_e32 v46, v46, v47
	v_pk_fma_f32 v[18:19], v[18:19], v[2:3], v[58:59] op_sel_hi:[1,0,1] neg_lo:[0,0,1] neg_hi:[0,0,1]
	v_add_f32_e32 v46, v46, v64
	v_pk_mul_f32 v[58:59], v[18:19], v[18:19]
	v_pk_mul_f32 v[62:63], v[128:129], v[62:63]
	v_add_f32_e32 v46, v46, v65
	v_pk_fma_f32 v[20:21], v[20:21], v[2:3], v[62:63] op_sel_hi:[1,0,1] neg_lo:[0,0,1] neg_hi:[0,0,1]
	v_add_f32_e32 v46, v46, v58
	v_pk_mul_f32 v[60:61], v[128:129], v[60:61]
	v_pk_mul_f32 v[62:63], v[20:21], v[20:21]
	v_add_f32_e32 v46, v46, v59
	v_pk_fma_f32 v[22:23], v[22:23], v[2:3], v[60:61] op_sel_hi:[1,0,1] neg_lo:[0,0,1] neg_hi:[0,0,1]
	v_add_f32_e32 v46, v46, v62
	v_pk_mul_f32 v[60:61], v[22:23], v[22:23]
	v_pk_mul_f32 v[12:13], v[128:129], v[12:13]
	v_pk_mul_f32 v[66:67], v[128:129], v[66:67]
	v_add_f32_e32 v46, v46, v63
	v_pk_fma_f32 v[12:13], v[26:27], v[2:3], v[12:13] op_sel_hi:[1,0,1] neg_lo:[0,0,1] neg_hi:[0,0,1]
	v_pk_fma_f32 v[2:3], v[24:25], v[2:3], v[66:67] op_sel_hi:[1,0,1] neg_lo:[0,0,1] neg_hi:[0,0,1]
	v_add_f32_e32 v46, v46, v60
	v_pk_mul_f32 v[24:25], v[2:3], v[2:3]
	v_add_f32_e32 v46, v46, v61
	v_add_f32_e32 v24, v46, v24
	v_pk_mul_f32 v[26:27], v[12:13], v[12:13]
	v_add_f32_e32 v24, v24, v25
	v_add_f32_e32 v24, v24, v26
	v_pk_mul_f32 v[14:15], v[6:7], v[6:7]
	v_add_f32_e32 v24, v24, v27
	v_add_f32_e32 v14, v24, v14
	v_pk_mul_f32 v[28:29], v[4:5], v[4:5]
	v_add_f32_e32 v14, v14, v15
	v_add_f32_e32 v14, v14, v28
	v_add_f32_e32 v24, v14, v29
	v_lshlrev_b32_e32 v14, 2, v72
	v_bitop3_b32 v14, v14, s33, v220 bitop3:0x6c
	ds_bpermute_b32 v25, v14, v24
	v_lshlrev_b32_e32 v14, 11, v1
	v_mov_b32_e32 v15, v0
	v_readlane_b32 s11, v237, 59
	v_lshl_add_u64 v[14:15], s[6:7], 0, v[14:15]
	s_waitcnt lgkmcnt(0)
; __device__ __forceinline__ float shx(float v, int o) { const int idx = (((int)otid() & 63) ^ o) << 2; return __builtin_bit_cast(float, __builtin_amdgcn_ds_bpermute(idx, __builtin_bit_cast(int, v))); }
; __device__ __forceinline__ unsigned pk2(float lo, float hi) { f32x2_t v = {lo, hi}; bf16x2_t b = __builtin_convertvector(v, bf16x2_t); return __builtin_bit_cast(unsigned, b); }
; template <bool DIFF>
; __device__ __forceinline__ void attn_unit(CA& A, int l, int b, int hh, int qb, LAS unsigned char* lds, float lam, float lam_init) {
;     ...
;             ss += shx(ss, 32);
;             const float rs = rsqrtf(ss * (1.0f / 64.0f) + EPS) * (1.0f - lam_init);
;             const float* og = A.diff_out_g + l * 64;
; #pragma unroll
;             for (int dt = 0; dt < 2; ++dt)
; #pragma unroll
;                 for (int g = 0; g < 4; ++g) { const int d = 32 * dt + 8 * g + 4 * hi;
;                     v2u w; w.x = pk2(o[dt][4 * g] * rs * og[d], o[dt][4 * g + 1] * rs * og[d + 1]); w.y = pk2(o[dt][4 * g + 2] * rs * og[d + 2], o[dt][4 * g + 3] * rs * og[d + 3]);
;                     *(v2u*)(MIX + orow * DM + hh * 64 + d) = w; }
	v_add_f32_e32 v1, v24, v25
	v_fmamk_f32 v1, v1, 0x3c800000, v216
	v_mul_f32_e32 v24, 0x4b800000, v1
	v_cmp_gt_f32_e32 vcc, s0, v1
	v_lshl_add_u64 v[14:15], v[14:15], 0, s[10:11]
	v_mov_b32_e32 v25, v0
	v_cndmask_b32_e32 v1, v1, v24, vcc
	v_rsq_f32_e32 v1, v1
	v_lshlrev_b32_e32 v24, 1, v131
	v_lshl_add_u64 v[14:15], v[14:15], 0, v[24:25]
	s_mov_b32 s7, s11
	v_mul_f32_e32 v24, 0x45800000, v1
	v_cndmask_b32_e32 v1, v1, v24, vcc
	v_mul_f32_e32 v24, v136, v1
	v_pk_mul_f32 v[26:27], v[32:33], v[24:25] op_sel_hi:[1,0]
	v_writelane_b32 v237, s6, 58
	s_waitcnt vmcnt(0)
	v_pk_mul_f32 v[8:9], v[8:9], v[26:27]
	v_pk_mul_f32 v[26:27], v[34:35], v[24:25] op_sel_hi:[1,0]
	v_writelane_b32 v237, s7, 59
	v_pk_mul_f32 v[10:11], v[10:11], v[26:27]
	s_mov_b32 s6, 0x7500000
	v_cvt_pk_bf16_f32 v8, v8, v9
	v_cvt_pk_bf16_f32 v9, v10, v11
	v_add_co_u32_e32 v10, vcc, s6, v14
	v_pk_mul_f32 v[26:27], v[36:37], v[24:25] op_sel_hi:[1,0]
	s_nop 0
	v_addc_co_u32_e32 v11, vcc, 0, v15, vcc
	global_store_dwordx2 v[10:11], v[8:9], off
	v_pk_mul_f32 v[28:29], v[38:39], v[24:25] op_sel_hi:[1,0]
	s_mov_b64 s[6:7], 0x7500000
	v_lshl_add_u64 v[14:15], v[14:15], 0, s[6:7]
	v_pk_mul_f32 v[16:17], v[16:17], v[24:25] op_sel_hi:[1,0]
	v_pk_mul_f32 v[18:19], v[18:19], v[24:25] op_sel_hi:[1,0]
	v_pk_mul_f32 v[2:3], v[2:3], v[24:25] op_sel_hi:[1,0]
	v_pk_mul_f32 v[12:13], v[12:13], v[24:25] op_sel_hi:[1,0]
	v_pk_mul_f32 v[4:5], v[4:5], v[24:25] op_sel_hi:[1,0]
	v_pk_mul_f32 v[148:149], v[148:149], v[26:27]
	v_pk_mul_f32 v[150:151], v[150:151], v[28:29]
	v_cvt_pk_bf16_f32 v148, v148, v149
	v_cvt_pk_bf16_f32 v149, v150, v151
	global_store_dwordx2 v[14:15], v[148:149], off offset:16
	v_pk_mul_f32 v[26:27], v[40:41], v[24:25] op_sel_hi:[1,0]
	v_pk_mul_f32 v[28:29], v[42:43], v[24:25] op_sel_hi:[1,0]
	v_pk_mul_f32 v[152:153], v[152:153], v[26:27]
	v_pk_mul_f32 v[154:155], v[28:29], v[154:155]
	v_cvt_pk_bf16_f32 v152, v152, v153
	v_cvt_pk_bf16_f32 v153, v154, v155
	global_store_dwordx2 v[14:15], v[152:153], off offset:32
	v_pk_mul_f32 v[26:27], v[44:45], v[24:25] op_sel_hi:[1,0]
	v_pk_mul_f32 v[28:29], v[30:31], v[24:25] op_sel_hi:[1,0]
	v_pk_mul_f32 v[156:157], v[26:27], v[156:157]
	v_pk_mul_f32 v[158:159], v[28:29], v[158:159]
	v_cvt_pk_bf16_f32 v156, v156, v157
	v_cvt_pk_bf16_f32 v157, v158, v159
	global_store_dwordx2 v[14:15], v[156:157], off offset:48
	v_pk_mul_f32 v[160:161], v[16:17], v[160:161]
	v_pk_mul_f32 v[162:163], v[18:19], v[162:163]
	v_cvt_pk_bf16_f32 v160, v160, v161
	v_cvt_pk_bf16_f32 v161, v162, v163
	global_store_dwordx2 v[14:15], v[160:161], off offset:64
	v_pk_mul_f32 v[16:17], v[20:21], v[24:25] op_sel_hi:[1,0]
	v_pk_mul_f32 v[18:19], v[22:23], v[24:25] op_sel_hi:[1,0]
	v_pk_mul_f32 v[164:165], v[16:17], v[164:165]
	v_pk_mul_f32 v[166:167], v[18:19], v[166:167]
	v_cvt_pk_bf16_f32 v164, v164, v165
	v_cvt_pk_bf16_f32 v165, v166, v167
	global_store_dwordx2 v[14:15], v[164:165], off offset:80
	v_pk_mul_f32 v[2:3], v[2:3], v[168:169]
	v_pk_mul_f32 v[168:169], v[12:13], v[170:171]
	v_cvt_pk_bf16_f32 v2, v2, v3
	v_cvt_pk_bf16_f32 v3, v168, v169
	global_store_dwordx2 v[14:15], v[2:3], off offset:96
	v_pk_mul_f32 v[2:3], v[6:7], v[24:25] op_sel_hi:[1,0]
	v_pk_mul_f32 v[4:5], v[4:5], v[174:175]
	v_pk_mul_f32 v[2:3], v[2:3], v[172:173]
	s_nop 0
	v_cvt_pk_bf16_f32 v2, v2, v3
	v_cvt_pk_bf16_f32 v3, v4, v5
	global_store_dwordx2 v[14:15], v[2:3], off offset:112

; #define LAS __attribute__((address_space(3)))
; __device__ __forceinline__ float fast_sigmoid(float x) { return __builtin_amdgcn_rcpf(1.0f + __builtin_amdgcn_exp2f(-x * LOG2E)); }
; __device__ __forceinline__ void p0_prologue(CA& A, LAS unsigned char* lds) {
;     ...
;     float* MOD = (float*)(A.ws + WS_MOD);
;     LAS float* cond = (LAS float*)(lds + 8 * 16384 - 16384);
;     for (int i = tid; i < 4 * DM; i += 512) { const float v = A.c[i]; cond[i] = v * fast_sigmoid(v); }
;     __syncthreads();
.LBB0_792:
	v_mov_b32_e32 v2, v179
	s_movk_i32 s4, 0x1000
	s_waitcnt lgkmcnt(0)
	v_readfirstlane_b32 s8, v2
	v_cmp_gt_i32_e32 vcc, s4, v2
	s_and_saveexec_b64 s[4:5], vcc
	s_mov_b64 s[10:11], 0x800
	s_cbranch_execz .LBB0_795
	v_readlane_b32 s6, v237, 63
	v_readlane_b32 s7, v236, 0
	s_load_dwordx2 s[6:7], s[6:7], 0x8
	s_add_i32 s9, 0, 0x1c000
	v_ashrrev_i32_e32 v3, 31, v2
	v_add_u32_e32 v1, 0xfffffe00, v2
	v_lshl_add_u32 v6, v2, 2, s9
	s_waitcnt lgkmcnt(0)
	v_lshl_add_u64 v[4:5], v[2:3], 2, s[6:7]
	s_mov_b64 s[6:7], 0x1000
	v_lshl_add_u64 v[138:139], v[4:5], 0, s[6:7]
	v_lshl_add_u64 v[140:141], v[138:139], 0, s[6:7]
	v_lshl_add_u64 v[142:143], v[140:141], 0, s[6:7]
	global_load_dword v130, v[4:5], off
	global_load_dword v131, v[4:5], off offset:2048
	global_load_dword v132, v[138:139], off
	global_load_dword v133, v[138:139], off offset:2048
	global_load_dword v134, v[140:141], off
	global_load_dword v135, v[140:141], off offset:2048
	global_load_dword v136, v[142:143], off
	global_load_dword v137, v[142:143], off offset:2048
	s_waitcnt vmcnt(7)
	v_mul_f32_e32 v7, 0xbfb8aa3b, v130
	v_exp_f32_e32 v7, v7
	s_nop 0
	v_add_f32_e32 v7, 1.0, v7
	v_rcp_f32_e32 v7, v7
	s_nop 0
	v_mul_f32_e32 v3, v130, v7
	ds_write_b32 v6, v3
	s_waitcnt vmcnt(6)
	v_mul_f32_e32 v7, 0xbfb8aa3b, v131
	v_exp_f32_e32 v7, v7
	s_nop 0
	v_add_f32_e32 v7, 1.0, v7
	v_rcp_f32_e32 v7, v7
	s_nop 0
	v_mul_f32_e32 v3, v131, v7
	ds_write_b32 v6, v3 offset:2048
	s_waitcnt vmcnt(5)
	v_mul_f32_e32 v7, 0xbfb8aa3b, v132
	v_exp_f32_e32 v7, v7
	s_nop 0
	v_add_f32_e32 v7, 1.0, v7
	v_rcp_f32_e32 v7, v7
	s_nop 0
	v_mul_f32_e32 v3, v132, v7
	ds_write_b32 v6, v3 offset:4096
	s_waitcnt vmcnt(4)
	v_mul_f32_e32 v7, 0xbfb8aa3b, v133
	v_exp_f32_e32 v7, v7
	s_nop 0
	v_add_f32_e32 v7, 1.0, v7
	v_rcp_f32_e32 v7, v7
	s_nop 0
	v_mul_f32_e32 v3, v133, v7
	ds_write_b32 v6, v3 offset:6144
	s_waitcnt vmcnt(3)
	v_mul_f32_e32 v7, 0xbfb8aa3b, v134
	v_exp_f32_e32 v7, v7
	s_nop 0
	v_add_f32_e32 v7, 1.0, v7
	v_rcp_f32_e32 v7, v7
	s_nop 0
	v_mul_f32_e32 v3, v134, v7
	ds_write_b32 v6, v3 offset:8192
	s_waitcnt vmcnt(2)
	v_mul_f32_e32 v7, 0xbfb8aa3b, v135
	v_exp_f32_e32 v7, v7
	s_nop 0
	v_add_f32_e32 v7, 1.0, v7
	v_rcp_f32_e32 v7, v7
	s_nop 0
	v_mul_f32_e32 v3, v135, v7
	ds_write_b32 v6, v3 offset:10240
	s_waitcnt vmcnt(1)
	v_mul_f32_e32 v7, 0xbfb8aa3b, v136
	v_exp_f32_e32 v7, v7
	s_nop 0
	v_add_f32_e32 v7, 1.0, v7
	v_rcp_f32_e32 v7, v7
	s_nop 0
	v_mul_f32_e32 v3, v136, v7
	ds_write_b32 v6, v3 offset:12288
	s_waitcnt vmcnt(0)
	v_mul_f32_e32 v7, 0xbfb8aa3b, v137
	v_exp_f32_e32 v7, v7
	s_nop 0
	v_add_f32_e32 v7, 1.0, v7
	v_rcp_f32_e32 v7, v7
	s_nop 0
	v_mul_f32_e32 v3, v137, v7
	ds_write_b32 v6, v3 offset:14336
